# diff-attention prompt softmax: packed f32 forms for bias fma, max subtraction and pairwise row sum (23 fewer VALU issues per wave and key tile)
# baseline (speedup 1.0000x reference)
.LBB0_1082:
	ds_read_b128 v[112:115], v124
	ds_read_b128 v[116:119], v124 offset:64
	ds_read_b128 v[120:123], v124 offset:128
	ds_read_b128 v[166:169], v124 offset:192
	ds_read_b128 v[170:173], v147 offset:8448
	ds_read_b128 v[174:177], v147 offset:8512
	ds_read_b128 v[178:181], v147 offset:8576
	ds_read_b128 v[182:185], v147 offset:8640
	s_add_i32 s29, s29, 1
	s_waitcnt lgkmcnt(7)
	v_mfma_f32_16x16x32_bf16 v[112:115], v[112:115], v[0:3], 0
	s_waitcnt lgkmcnt(6)
	v_mfma_f32_16x16x32_bf16 v[112:115], v[116:119], v[4:7], v[112:115]
	s_waitcnt lgkmcnt(5)
	v_mfma_f32_16x16x32_bf16 v[112:115], v[120:123], v[8:11], v[112:115]
	s_waitcnt lgkmcnt(4)
	v_mfma_f32_16x16x32_bf16 v[166:169], v[166:169], v[12:15], v[112:115]
	s_nop 5
	ds_read_b128 v[112:115], v147 offset:16896
	ds_read_b128 v[116:119], v147 offset:16960
	ds_read_b128 v[186:189], v147 offset:17024
	ds_read_b128 v[190:193], v147 offset:17088
	s_waitcnt lgkmcnt(7)
	v_mfma_f32_16x16x32_bf16 v[120:123], v[170:173], v[0:3], 0
	s_waitcnt lgkmcnt(6)
	v_mfma_f32_16x16x32_bf16 v[120:123], v[174:177], v[4:7], v[120:123]
	s_waitcnt lgkmcnt(5)
	v_mfma_f32_16x16x32_bf16 v[120:123], v[178:181], v[8:11], v[120:123]
	s_waitcnt lgkmcnt(4)
	v_mfma_f32_16x16x32_bf16 v[120:123], v[182:185], v[12:15], v[120:123]
	ds_read_b128 v[170:173], v148
	ds_read_b128 v[174:177], v148 offset:64
	ds_read_b128 v[178:181], v148 offset:128
	ds_read_b128 v[182:185], v148 offset:192
	s_waitcnt lgkmcnt(7)
	v_mfma_f32_16x16x32_bf16 v[112:115], v[112:115], v[0:3], 0
	s_waitcnt lgkmcnt(6)
	v_mfma_f32_16x16x32_bf16 v[112:115], v[116:119], v[4:7], v[112:115]
	s_waitcnt lgkmcnt(5)
	v_mfma_f32_16x16x32_bf16 v[112:115], v[186:189], v[8:11], v[112:115]
	s_waitcnt lgkmcnt(4)
	v_mfma_f32_16x16x32_bf16 v[116:119], v[190:193], v[12:15], v[112:115]
	s_waitcnt lgkmcnt(3)
	v_mfma_f32_16x16x32_bf16 v[112:115], v[170:173], v[0:3], 0
	s_waitcnt lgkmcnt(2)
	v_mfma_f32_16x16x32_bf16 v[112:115], v[174:177], v[4:7], v[112:115]
	s_waitcnt lgkmcnt(1)
	v_mfma_f32_16x16x32_bf16 v[112:115], v[178:181], v[8:11], v[112:115]
	s_waitcnt lgkmcnt(0)
	v_mfma_f32_16x16x32_bf16 v[112:115], v[182:185], v[12:15], v[112:115]
	ds_read_b128 v[186:189], v143 offset:15360
	ds_read_b128 v[190:193], v143 offset:17920
	s_mov_b32 s26, 0xff800000
	v_sub_f32_e32 v156, v156, v220
	v_pk_fma_f32 v[170:171], v[166:167], v[126:127], v[204:205] op_sel_hi:[1,0,1] neg_lo:[0,0,1] neg_hi:[0,0,1]
	v_pk_fma_f32 v[172:173], v[168:169], v[126:127], v[206:207] op_sel_hi:[1,0,1] neg_lo:[0,0,1] neg_hi:[0,0,1]
	v_pk_fma_f32 v[174:175], v[120:121], v[126:127], v[208:209] op_sel_hi:[1,0,1] neg_lo:[0,0,1] neg_hi:[0,0,1]
	v_pk_fma_f32 v[176:177], v[122:123], v[126:127], v[210:211] op_sel_hi:[1,0,1] neg_lo:[0,0,1] neg_hi:[0,0,1]
	v_pk_fma_f32 v[178:179], v[116:117], v[126:127], v[212:213] op_sel_hi:[1,0,1] neg_lo:[0,0,1] neg_hi:[0,0,1]
	v_pk_fma_f32 v[180:181], v[118:119], v[126:127], v[214:215] op_sel_hi:[1,0,1] neg_lo:[0,0,1] neg_hi:[0,0,1]
	v_pk_fma_f32 v[182:183], v[112:113], v[126:127], v[216:217] op_sel_hi:[1,0,1] neg_lo:[0,0,1] neg_hi:[0,0,1]
	v_pk_fma_f32 v[184:185], v[114:115], v[126:127], v[218:219] op_sel_hi:[1,0,1] neg_lo:[0,0,1] neg_hi:[0,0,1]
	v_max3_f32 v112, v170, v171, v172
	v_max3_f32 v112, v112, v173, v174
	v_max3_f32 v112, v112, v175, v176
	v_max3_f32 v112, v112, v177, v178
	v_max3_f32 v112, v112, v179, v180
	v_max3_f32 v112, v112, v181, v182
	v_max3_f32 v112, v112, v183, v184
	v_max_f32_e32 v112, v112, v185
	ds_bpermute_b32 v115, v139, v112
	s_waitcnt lgkmcnt(0)
	v_max_f32_e32 v115, v115, v115
	v_max_f32_e32 v112, v112, v115
	ds_bpermute_b32 v115, v140, v112
	s_waitcnt lgkmcnt(0)
	v_max3_f32 v112, v156, v112, v115
	v_sub_f32_e32 v115, v156, v112
	v_exp_f32_e32 v118, v115
	v_pk_add_f32 v[170:171], v[170:171], v[112:113] op_sel_hi:[1,0] neg_lo:[0,1] neg_hi:[0,1]
	v_pk_add_f32 v[172:173], v[172:173], v[112:113] op_sel_hi:[1,0] neg_lo:[0,1] neg_hi:[0,1]
	v_pk_add_f32 v[174:175], v[174:175], v[112:113] op_sel_hi:[1,0] neg_lo:[0,1] neg_hi:[0,1]
	v_pk_add_f32 v[176:177], v[176:177], v[112:113] op_sel_hi:[1,0] neg_lo:[0,1] neg_hi:[0,1]
	v_pk_add_f32 v[178:179], v[178:179], v[112:113] op_sel_hi:[1,0] neg_lo:[0,1] neg_hi:[0,1]
	v_pk_add_f32 v[180:181], v[180:181], v[112:113] op_sel_hi:[1,0] neg_lo:[0,1] neg_hi:[0,1]
	v_pk_add_f32 v[182:183], v[182:183], v[112:113] op_sel_hi:[1,0] neg_lo:[0,1] neg_hi:[0,1]
	v_pk_add_f32 v[184:185], v[184:185], v[112:113] op_sel_hi:[1,0] neg_lo:[0,1] neg_hi:[0,1]
	v_exp_f32_e32 v170, v170
	v_exp_f32_e32 v171, v171
	v_exp_f32_e32 v172, v172
	v_exp_f32_e32 v173, v173
	v_exp_f32_e32 v174, v174
	v_exp_f32_e32 v175, v175
	v_exp_f32_e32 v176, v176
	v_exp_f32_e32 v177, v177
	v_exp_f32_e32 v178, v178
	v_exp_f32_e32 v179, v179
	v_exp_f32_e32 v180, v180
	v_exp_f32_e32 v181, v181
	v_exp_f32_e32 v182, v182
	v_exp_f32_e32 v183, v183
	v_exp_f32_e32 v184, v184
	v_exp_f32_e32 v185, v185
	s_nop 0
	v_pk_add_f32 v[166:167], v[170:171], v[172:173]
	v_pk_add_f32 v[168:169], v[174:175], v[176:177]
	v_pk_add_f32 v[120:121], v[178:179], v[180:181]
	v_pk_add_f32 v[122:123], v[182:183], v[184:185]
	v_pk_add_f32 v[166:167], v[166:167], v[168:169]
	v_pk_add_f32 v[120:121], v[120:121], v[122:123]
	v_pk_add_f32 v[166:167], v[166:167], v[120:121]
	v_add_f32_e32 v113, v166, v167
	v_fmac_f32_e32 v113, v155, v118
	v_pk_mul_f32 v[110:111], v[110:111], v[118:119] op_sel_hi:[1,0]
	v_pk_mul_f32 v[108:109], v[108:109], v[118:119] op_sel_hi:[1,0]
	v_pk_mul_f32 v[106:107], v[106:107], v[118:119] op_sel_hi:[1,0]
	v_pk_mul_f32 v[104:105], v[104:105], v[118:119] op_sel_hi:[1,0]
	v_pk_mul_f32 v[102:103], v[102:103], v[118:119] op_sel_hi:[1,0]
	v_pk_mul_f32 v[100:101], v[100:101], v[118:119] op_sel_hi:[1,0]
	v_pk_mul_f32 v[116:117], v[94:95], v[118:119] op_sel_hi:[1,0]
	v_pk_mul_f32 v[114:115], v[92:93], v[118:119] op_sel_hi:[1,0]
	v_pk_mul_f32 v[94:95], v[98:99], v[118:119] op_sel_hi:[1,0]
	v_pk_mul_f32 v[92:93], v[96:97], v[118:119] op_sel_hi:[1,0]
	v_pk_mul_f32 v[90:91], v[90:91], v[118:119] op_sel_hi:[1,0]
	v_pk_mul_f32 v[88:89], v[88:89], v[118:119] op_sel_hi:[1,0]
	v_pk_mul_f32 v[86:87], v[86:87], v[118:119] op_sel_hi:[1,0]
	v_pk_mul_f32 v[84:85], v[84:85], v[118:119] op_sel_hi:[1,0]
	v_pk_mul_f32 v[82:83], v[82:83], v[118:119] op_sel_hi:[1,0]
	v_pk_mul_f32 v[80:81], v[80:81], v[118:119] op_sel_hi:[1,0]
	v_pk_mul_f32 v[78:79], v[78:79], v[118:119] op_sel_hi:[1,0]
	v_pk_mul_f32 v[76:77], v[76:77], v[118:119] op_sel_hi:[1,0]
	v_pk_mul_f32 v[74:75], v[74:75], v[118:119] op_sel_hi:[1,0]
	v_pk_mul_f32 v[72:73], v[72:73], v[118:119] op_sel_hi:[1,0]
	v_pk_mul_f32 v[70:71], v[70:71], v[118:119] op_sel_hi:[1,0]
	v_pk_mul_f32 v[68:69], v[68:69], v[118:119] op_sel_hi:[1,0]
	v_pk_mul_f32 v[66:67], v[66:67], v[118:119] op_sel_hi:[1,0]
	v_pk_mul_f32 v[64:65], v[64:65], v[118:119] op_sel_hi:[1,0]
	v_pk_mul_f32 v[62:63], v[62:63], v[118:119] op_sel_hi:[1,0]
	v_pk_mul_f32 v[60:61], v[60:61], v[118:119] op_sel_hi:[1,0]
	v_pk_mul_f32 v[58:59], v[58:59], v[118:119] op_sel_hi:[1,0]
	v_pk_mul_f32 v[56:57], v[56:57], v[118:119] op_sel_hi:[1,0]
	v_pk_mul_f32 v[54:55], v[54:55], v[118:119] op_sel_hi:[1,0]
	v_pk_mul_f32 v[52:53], v[52:53], v[118:119] op_sel_hi:[1,0]
	v_pk_mul_f32 v[98:99], v[50:51], v[118:119] op_sel_hi:[1,0]
	v_pk_mul_f32 v[96:97], v[48:49], v[118:119] op_sel_hi:[1,0]
	v_cvt_pk_bf16_f32 v118, v170, v171
	v_cvt_pk_bf16_f32 v119, v172, v173
	v_cvt_pk_bf16_f32 v120, v174, v175
	v_cvt_pk_bf16_f32 v121, v176, v177
	v_cvt_pk_bf16_f32 v48, v178, v179
	v_cvt_pk_bf16_f32 v49, v180, v181
	v_cvt_pk_bf16_f32 v50, v182, v183
	v_cvt_pk_bf16_f32 v51, v184, v185
	ds_read_b128 v[156:159], v143 offset:0
	ds_read_b128 v[166:169], v143 offset:2560
	ds_read_b128 v[170:173], v143 offset:5120
	ds_read_b128 v[174:177], v143 offset:7680
	ds_read_b128 v[178:181], v143 offset:10240
	ds_read_b128 v[182:185], v143 offset:12800
	s_waitcnt lgkmcnt(5)
	v_mfma_f32_16x16x32_bf16 v[108:111], v[156:159], v[118:121], v[108:111]
	s_waitcnt lgkmcnt(4)
	v_mfma_f32_16x16x32_bf16 v[104:107], v[166:169], v[118:121], v[104:107]
	s_waitcnt lgkmcnt(3)
	v_mfma_f32_16x16x32_bf16 v[100:103], v[170:173], v[118:121], v[100:103]
	s_waitcnt lgkmcnt(2)
	v_mfma_f32_16x16x32_bf16 v[114:117], v[174:177], v[118:121], v[114:117]
	ds_read_b128 v[156:159], v143 offset:20480
	ds_read_b128 v[166:169], v143 offset:23040
	ds_read_b128 v[170:173], v143 offset:25600
	ds_read_b128 v[174:177], v143 offset:28160
	s_waitcnt lgkmcnt(4)
	v_mfma_f32_16x16x32_bf16 v[88:91], v[182:185], v[118:121], v[88:91]
	v_mfma_f32_16x16x32_bf16 v[84:87], v[186:189], v[118:121], v[84:87]
	v_mfma_f32_16x16x32_bf16 v[80:83], v[190:193], v[118:121], v[80:83]
	v_mfma_f32_16x16x32_bf16 v[178:181], v[178:181], v[118:121], v[92:95]
	s_nop 2
	ds_read_b128 v[92:95], v143 offset:30720
	ds_read_b128 v[182:185], v143 offset:33280
	ds_read_b128 v[186:189], v143 offset:35840
	ds_read_b128 v[190:193], v143 offset:38400
	s_waitcnt lgkmcnt(7)
	v_mfma_f32_16x16x32_bf16 v[76:79], v[156:159], v[118:121], v[76:79]
	s_waitcnt lgkmcnt(6)
	v_mfma_f32_16x16x32_bf16 v[72:75], v[166:169], v[118:121], v[72:75]
	s_waitcnt lgkmcnt(5)
	v_mfma_f32_16x16x32_bf16 v[68:71], v[170:173], v[118:121], v[68:71]
	s_waitcnt lgkmcnt(4)
	v_mfma_f32_16x16x32_bf16 v[64:67], v[174:177], v[118:121], v[64:67]
	ds_read_b128 v[156:159], v143 offset:64
	ds_read_b128 v[166:169], v143 offset:2624
	ds_read_b128 v[170:173], v143 offset:5184
	ds_read_b128 v[174:177], v143 offset:7744
	s_waitcnt lgkmcnt(7)
	v_mfma_f32_16x16x32_bf16 v[60:63], v[92:95], v[118:121], v[60:63]
	s_waitcnt lgkmcnt(6)
	v_mfma_f32_16x16x32_bf16 v[56:59], v[182:185], v[118:121], v[56:59]
	s_waitcnt lgkmcnt(5)
	v_mfma_f32_16x16x32_bf16 v[52:55], v[186:189], v[118:121], v[52:55]
	s_waitcnt lgkmcnt(4)
	v_mfma_f32_16x16x32_bf16 v[118:121], v[190:193], v[118:121], v[96:99]
	s_nop 2
	ds_read_b128 v[96:99], v143 offset:10304
	ds_read_b128 v[182:185], v143 offset:12864
	ds_read_b128 v[186:189], v143 offset:15424
	ds_read_b128 v[190:193], v143 offset:17984
	s_waitcnt lgkmcnt(7)
	v_mfma_f32_16x16x32_bf16 v[108:111], v[156:159], v[48:51], v[108:111]
	s_waitcnt lgkmcnt(6)
	v_mfma_f32_16x16x32_bf16 v[104:107], v[166:169], v[48:51], v[104:107]
	s_waitcnt lgkmcnt(5)
	v_mfma_f32_16x16x32_bf16 v[100:103], v[170:173], v[48:51], v[100:103]
	s_waitcnt lgkmcnt(4)
	v_mfma_f32_16x16x32_bf16 v[92:95], v[174:177], v[48:51], v[114:117]
	s_nop 2
	ds_read_b128 v[114:117], v143 offset:20544
	ds_read_b128 v[156:159], v143 offset:23104
	ds_read_b128 v[166:169], v143 offset:25664
	ds_read_b128 v[170:173], v143 offset:28224
	s_waitcnt lgkmcnt(7)
	v_mfma_f32_16x16x32_bf16 v[96:99], v[96:99], v[48:51], v[178:181]
	s_waitcnt lgkmcnt(6)
	v_mfma_f32_16x16x32_bf16 v[88:91], v[182:185], v[48:51], v[88:91]
	s_waitcnt lgkmcnt(5)
	v_mfma_f32_16x16x32_bf16 v[84:87], v[186:189], v[48:51], v[84:87]
	s_waitcnt lgkmcnt(4)
	v_mfma_f32_16x16x32_bf16 v[80:83], v[190:193], v[48:51], v[80:83]
	ds_read_b128 v[174:177], v143 offset:30784
	ds_read_b128 v[178:181], v143 offset:33344
	ds_read_b128 v[182:185], v143 offset:35904
	ds_read_b128 v[186:189], v143 offset:38464
	s_waitcnt lgkmcnt(7)
	v_mfma_f32_16x16x32_bf16 v[76:79], v[114:117], v[48:51], v[76:79]
	s_waitcnt lgkmcnt(6)
	v_mfma_f32_16x16x32_bf16 v[72:75], v[156:159], v[48:51], v[72:75]
	s_waitcnt lgkmcnt(5)
	v_mfma_f32_16x16x32_bf16 v[68:71], v[166:169], v[48:51], v[68:71]
	s_waitcnt lgkmcnt(4)
	v_mfma_f32_16x16x32_bf16 v[64:67], v[170:173], v[48:51], v[64:67]
	s_waitcnt lgkmcnt(3)
	v_mfma_f32_16x16x32_bf16 v[60:63], v[174:177], v[48:51], v[60:63]
	s_waitcnt lgkmcnt(2)
	v_mfma_f32_16x16x32_bf16 v[56:59], v[178:181], v[48:51], v[56:59]
	s_waitcnt lgkmcnt(1)
	v_mfma_f32_16x16x32_bf16 v[52:55], v[182:185], v[48:51], v[52:55]
	s_waitcnt lgkmcnt(0)
	v_mfma_f32_16x16x32_bf16 v[48:51], v[186:189], v[48:51], v[118:121]
	s_mov_b64 s[34:35], 0x80
	v_lshl_add_u64 v[132:133], v[132:133], 0, s[34:35]
	s_mov_b64 s[34:35], 0x40000
	v_subrev_u32_e32 v144, 64, v144
	s_cmp_eq_u32 s30, s29
	v_lshl_add_u64 v[136:137], v[136:137], 0, s[34:35]
	s_cbranch_scc1 .LBB0_1084
	v_mov_b32_e32 v155, v113
	v_mov_b32_e32 v156, v112
	s_branch .LBB0_1080
